# combined: z-gate load batching + QK K-fragment prefetch + early K/V LDS staging + P3 order swap on odd workgroups + workgroup-local barrier between compress GEMM and its second stage
# speedup vs baseline: 1.0416x; 1.0017x over previous
; __device__ __forceinline__ unsigned xb_add(unsigned* p, unsigned v) { return __hip_atomic_fetch_add(p, v, __ATOMIC_RELAXED, __HIP_MEMORY_SCOPE_AGENT); }
; __device__ __forceinline__ void xcd_barrier(const XcdBarrier& b) {
;     asm volatile("s_waitcnt vmcnt(0)" ::: "memory");
;     __syncthreads();
;     if (threadIdx.x == 0) {
;         unsigned* bar = b.bar;
;         __builtin_amdgcn_s_waitcnt(0);
;         unsigned nloc = b.st[0], nx = b.st[1];
;         if (nloc == 0u) { xcd_barrier_complete(bar, b.x, nloc, nx); b.st[0] = nloc; b.st[1] = nx; }
;         const unsigned old = xb_add(&bar[XB_XSUB(b.x)], 1u);
.LBB0_511:
	v_readlane_b32 s0, v254, 12
	s_add_i32 s0, s0, 3
	v_readlane_b32 s1, v253, 9
	s_cmp_ge_i32 s0, s1
	s_cbranch_scc1 .LBB0_565
	s_waitcnt vmcnt(0)
	s_waitcnt lgkmcnt(0)
	s_barrier
	s_mov_b64 s[2:3], exec
	v_readlane_b32 s4, v253, 6
	v_readlane_b32 s5, v253, 7
	s_and_b64 s[4:5], s[2:3], s[4:5]
	s_mov_b64 exec, s[4:5]
	s_branch .LBB0_564
	v_readlane_b32 s1, v254, 5
	s_waitcnt vmcnt(0) expcnt(0) lgkmcnt(0)
	s_nop 0
	v_mov_b32_e32 v0, s1
	ds_read_b32 v2, v0
	v_readlane_b32 s1, v254, 6
	s_waitcnt lgkmcnt(0)
	v_cmp_ne_u32_e32 vcc, 0, v2
	v_mov_b32_e32 v0, s1
	ds_read_b32 v0, v0
	s_cbranch_vccnz .LBB0_528
	v_readlane_b32 s6, v253, 10
	v_readlane_b32 s7, v253, 11
	s_load_dwordx2 s[4:5], s[6:7], 0x4
	s_mov_b32 s10, 1
	s_waitcnt lgkmcnt(0)
	s_mul_i32 s1, s4, s22
	s_mul_i32 s1, s1, s5
	s_branch .LBB0_516
